# band items: side-loaded tile 0 parked in a third LDS region (above both halves' stage pairs), the extra workgroup barrier per item removed
# baseline (speedup 1.0000x reference)
; #define LAS __attribute__((address_space(3)))
; #define MFMA(a, b, c) __builtin_amdgcn_mfma_f32_32x32x16_bf16((a), (b), (c), 0, 0, 0)
; template <int DVT>
; DI void attn_step(lptr sKw, int kpitch, lptr sV, int vpitch, const bf16x8 (&qf)[4], float& m, float& l, f32x16 (&O)[DVT],
;                   const LAS float* tb, bool far, float cfar, int lane) {
;     ...
;         kf[2 * s] = *(const LAS bf16x8*)(sKw + r * kpitch + (16 * s + 8 * h) * 2);
;         kf[2 * s + 1] = *(const LAS bf16x8*)(sKw + (32 + r) * kpitch + (16 * s + 8 * h) * 2);
;     }
;     __builtin_amdgcn_sched_barrier(0);
; #pragma unroll
;     for (int s = 0; s < 4; ++s) { p0 = MFMA(kf[2 * s], qf[s], p0); p1 = MFMA(kf[2 * s + 1], qf[s], p1); }
;     const int i16 = lane & 15, q = i16 >> 2, pp = i16 & 3, blk = (lane >> 4) & 1;
;     lptr vb = sV + (4 * h + q) * vpitch + (16 * blk + 4 * pp) * 2;
; DI void band_item(const Params& P, char* lds_blk, int layer, int bp) {
;     ...
;     for (int kt = kt0; kt < 4; ++kt) {
;         if (kt + 1 < 4) gload(kt + 1);
;         __syncthreads();
;         const int b = (kt - kt0) & 1;
;         const bool active = (64 * kt <= 128 + 32 * w + 31) && (64 * kt + 63 >= 128 + 32 * w - maxd);
;         if (active) {
;             const LAS float* tb = (const LAS float*)btab + (qpos - 64 * kt - 4 * h + 128 - 63);
;             lptr sK = (lptr)lds + b * (2 * 64 * GP);
;             attn_step<2>(sK, GP, sK + 64 * GP, GP, qf, m, l, O, tb, false, 0.f, lane);
.Lb3_noovr:
	s_add_i32 s0, s64, 63
	s_add_i32 s65, s65, 1
	v_cmp_le_u32_e32 vcc, s64, v126
	v_cmp_ge_u32_e64 s[0:1], s0, v128
	s_and_b32 s70, s65, 1
	s_and_b32 s70, s70, s101
	s_and_b64 s[72:73], vcc, s[0:1]
	s_waitcnt lgkmcnt(0)
	s_barrier
	s_and_saveexec_b64 s[0:1], s[72:73]
	s_cbranch_execz .LBB0_220
	s_mul_i32 s71, s70, 0x4800
	s_cmp_eq_u32 s101, 0
	s_cbranch_scc0 .Lb3_s3
	v_readfirstlane_b32 s71, v174
	s_nop 3
	s_lshr_b32 s71, s71, 8
	s_mul_i32 s71, s71, 0x5800
	s_sub_i32 s71, 0x14000, s71
.Lb3_s3:
	v_add_u32_e32 v98, s71, v125
	v_add3_u32 v38, v98, v127, v112
	v_add3_u32 v39, v98, v129, v112
	ds_read_b128 v[34:37], v38
	ds_read_b128 v[50:53], v38 offset:32
	ds_read_b128 v[54:57], v39
	ds_read_b128 v[136:139], v39 offset:32
	ds_read_b128 v[58:61], v38 offset:64
	ds_read_b128 v[62:65], v38 offset:96
	ds_read_b128 v[140:143], v39 offset:64
	ds_read_b128 v[144:147], v39 offset:96
	s_waitcnt lgkmcnt(7)
	v_mfma_f32_32x32x16_bf16 v[34:49], v[34:37], v[66:69], 0
	s_waitcnt lgkmcnt(6)
	v_mfma_f32_32x32x16_bf16 v[34:49], v[50:53], v[70:73], v[34:49]
	v_add_u32_e32 v50, v98, v131
	v_add_u32_e32 v135, v50, v132
	ds_read_b64_tr_b16 v[102:103], v135 offset:9216
	ds_read_b64_tr_b16 v[104:105], v135 offset:10368
	ds_read_b64_tr_b16 v[100:101], v135 offset:10432
	ds_read_b64_tr_b16 v[98:99], v135 offset:9280
	s_waitcnt lgkmcnt(7)
	v_mfma_f32_32x32x16_bf16 v[34:49], v[58:61], v[74:77], v[34:49]
	s_waitcnt lgkmcnt(6)
	v_mfma_f32_32x32x16_bf16 v[34:49], v[62:65], v[78:81], v[34:49]
	v_mfma_f32_32x32x16_bf16 v[50:65], v[54:57], v[66:69], 0
	v_mfma_f32_32x32x16_bf16 v[50:65], v[136:139], v[70:73], v[50:65]
	ds_read2_b32 v[136:137], v134 offset0:58 offset1:59
	ds_read2_b32 v[138:139], v134 offset0:56 offset1:57
	ds_read2_b32 v[148:149], v134 offset0:50 offset1:51
	ds_read2_b32 v[150:151], v134 offset0:48 offset1:49
	ds_read2_b32 v[152:153], v134 offset0:26 offset1:27
	ds_read2_b32 v[154:155], v134 offset0:24 offset1:25
	ds_read2_b32 v[156:157], v134 offset0:18 offset1:19
	ds_read2_b32 v[158:159], v134 offset0:16 offset1:17
	s_waitcnt lgkmcnt(13)
	v_mfma_f32_32x32x16_bf16 v[50:65], v[140:143], v[74:77], v[50:65]
	ds_read2_b32 v[140:141], v134 offset0:42 offset1:43
	ds_read2_b32 v[142:143], v134 offset0:40 offset1:41
	ds_read2_b32 v[160:161], v134 offset0:34 offset1:35
	ds_read2_b32 v[162:163], v134 offset0:32 offset1:33
	ds_read2_b32 v[164:165], v134 offset0:10 offset1:11
	ds_read2_b32 v[166:167], v134 offset0:8 offset1:9
	ds_read2_b32 v[168:169], v134 offset0:2 offset1:3
	ds_read2_b32 v[170:171], v134 offset1:1
	s_waitcnt lgkmcnt(15)
	v_mfma_f32_32x32x16_bf16 v[50:65], v[144:147], v[78:81], v[50:65]
	s_waitcnt lgkmcnt(0)
	v_fmamk_f32 v137, v34, 0x3e38aa3b, v137
	v_fmamk_f32 v35, v35, 0x3e38aa3b, v136
	v_fmamk_f32 v36, v36, 0x3e38aa3b, v139
	v_fmamk_f32 v37, v37, 0x3e38aa3b, v138
	v_fmamk_f32 v38, v38, 0x3e38aa3b, v149
	v_fmamk_f32 v39, v39, 0x3e38aa3b, v148
	v_fmamk_f32 v40, v40, 0x3e38aa3b, v151
	v_fmamk_f32 v41, v41, 0x3e38aa3b, v150
	v_fmamk_f32 v42, v42, 0x3e38aa3b, v141
	v_fmamk_f32 v43, v43, 0x3e38aa3b, v140
	v_fmamk_f32 v44, v44, 0x3e38aa3b, v143
	v_fmamk_f32 v45, v45, 0x3e38aa3b, v142
	v_fmamk_f32 v46, v46, 0x3e38aa3b, v161
	v_fmamk_f32 v47, v47, 0x3e38aa3b, v160
	v_fmamk_f32 v48, v48, 0x3e38aa3b, v163
	v_fmamk_f32 v49, v49, 0x3e38aa3b, v162
	v_max3_f32 v34, v137, v35, v36
	v_max3_f32 v136, v37, v38, v39
	v_max3_f32 v34, v34, v40, v41
	v_max3_f32 v136, v136, v42, v43
	v_max3_f32 v34, v34, v44, v45
	v_max3_f32 v136, v136, v46, v47
	v_max3_f32 v34, v34, v48, v49
	v_fmamk_f32 v50, v50, 0x3e38aa3b, v153
	v_fmamk_f32 v51, v51, 0x3e38aa3b, v152
	v_fmamk_f32 v52, v52, 0x3e38aa3b, v155
	v_fmamk_f32 v53, v53, 0x3e38aa3b, v154
	v_fmamk_f32 v54, v54, 0x3e38aa3b, v157
	v_fmamk_f32 v55, v55, 0x3e38aa3b, v156
	v_fmamk_f32 v56, v56, 0x3e38aa3b, v159
	v_fmamk_f32 v57, v57, 0x3e38aa3b, v158
	v_fmamk_f32 v58, v58, 0x3e38aa3b, v165
	v_fmamk_f32 v59, v59, 0x3e38aa3b, v164
	v_fmamk_f32 v60, v60, 0x3e38aa3b, v167
	v_fmamk_f32 v61, v61, 0x3e38aa3b, v166
	v_fmamk_f32 v62, v62, 0x3e38aa3b, v169
	v_fmamk_f32 v63, v63, 0x3e38aa3b, v168
	v_fmamk_f32 v64, v64, 0x3e38aa3b, v171
	v_fmamk_f32 v65, v65, 0x3e38aa3b, v170
	v_max3_f32 v34, v34, v50, v51
	v_max3_f32 v136, v136, v52, v53
	v_max3_f32 v34, v34, v54, v55
	v_max3_f32 v136, v136, v56, v57
	v_max3_f32 v34, v34, v58, v59
	v_max3_f32 v136, v136, v60, v61
	v_max3_f32 v34, v34, v62, v63
	v_max3_f32 v136, v136, v64, v65
	s_nop 0
	v_max_f32_e32 v136, v136, v136
	v_max_f32_e32 v34, v34, v34
	v_max_f32_e32 v34, v34, v136
	v_mov_b32_e32 v136, v34
	s_nop 1
	v_permlane32_swap_b32_e32 v34, v136
	v_max_f32_e32 v136, v136, v136
	v_max_f32_e32 v34, v34, v34
	v_max_f32_e32 v34, v34, v136
	v_sub_f32_e32 v136, v34, v133
	v_cmp_lt_f32_e32 vcc, s45, v136
	v_max_f32_e32 v34, v133, v34
	s_nop 0
	v_cndmask_b32_e32 v34, v133, v34, vcc
	v_sub_f32 v136, v137, v34
	v_sub_f32 v50, v50, v34
	v_sub_f32 v51, v51, v34
	v_sub_f32 v36, v36, v34
	v_sub_f32 v52, v52, v34
	v_sub_f32 v53, v53, v34
	v_sub_f32 v54, v54, v34
	v_sub_f32 v39, v39, v34
	v_sub_f32 v55, v55, v34
	v_sub_f32 v40, v40, v34
	v_sub_f32 v56, v56, v34
	v_sub_f32 v57, v57, v34
	v_sub_f32 v58, v58, v34
	v_sub_f32 v43, v43, v34
	v_sub_f32 v44, v44, v34
	v_sub_f32 v47, v47, v34
	v_sub_f32 v48, v48, v34
	v_sub_f32 v137, v35, v34
	v_sub_f32 v138, v37, v34
	v_sub_f32 v139, v38, v34
	v_sub_f32 v140, v41, v34
	v_sub_f32 v141, v42, v34
	v_sub_f32 v142, v59, v34
	v_sub_f32 v143, v60, v34
	v_sub_f32 v144, v45, v34
	v_sub_f32 v145, v61, v34
	v_sub_f32 v146, v46, v34
	v_sub_f32 v147, v62, v34
	v_sub_f32 v148, v63, v34
	v_sub_f32 v149, v64, v34
	v_sub_f32 v150, v49, v34
	v_sub_f32 v151, v65, v34
	s_nop 0
	v_exp_f32_e32 v59, v136
	v_exp_f32_e32 v35, v50
	v_exp_f32_e32 v60, v137
	v_exp_f32_e32 v37, v51
	v_exp_f32_e32 v61, v36
	v_exp_f32_e32 v38, v52
	v_exp_f32_e32 v62, v138
	v_exp_f32_e32 v41, v53
	v_exp_f32_e32 v63, v139
	v_exp_f32_e32 v42, v54
	v_exp_f32_e32 v64, v39
	v_exp_f32_e32 v45, v55
	v_exp_f32_e32 v65, v40
	v_exp_f32_e32 v46, v56
	v_exp_f32_e32 v136, v140
	v_exp_f32_e32 v49, v57
	v_exp_f32_e32 v51, v141
	v_exp_f32_e32 v36, v58
	v_exp_f32_e32 v52, v43
	v_exp_f32_e32 v39, v142
	v_exp_f32_e32 v53, v44
	v_exp_f32_e32 v40, v143
	v_exp_f32_e32 v54, v144
	v_exp_f32_e32 v43, v145
	v_exp_f32_e32 v55, v146
	v_exp_f32_e32 v44, v147
	v_exp_f32_e32 v56, v47
	v_exp_f32_e32 v47, v148
	v_exp_f32_e32 v57, v48
	v_exp_f32_e32 v48, v149
	v_exp_f32_e32 v58, v150
	v_exp_f32_e32 v50, v151
	v_add_f32 v137, v59, v35
	v_add_f32 v138, v51, v36
	v_add_f32 v139, v52, v39
	v_add_f32 v140, v53, v40
	v_add_f32 v141, v54, v43
	v_add_f32 v142, v55, v44
	s_nop 1
	s_nop 0
	v_add_f32 v137, v137, v138
	v_add_f32 v138, v60, v37
	v_add_f32 v143, v56, v47
	v_add_f32 v144, v57, v48
	v_cmp_neq_f32_e32 vcc, v34, v133
	v_add_f32 v138, v138, v139
	v_add_f32 v139, v61, v38
	v_add_f32 v145, v58, v50
	s_nop 0
	v_add_f32 v139, v139, v140
	v_add_f32 v140, v62, v41
	v_add_f32 v137, v137, v138
	s_nop 0
	v_add_f32 v140, v140, v141
	v_add_f32 v141, v63, v42
	s_nop 0
	v_add_f32 v141, v141, v142
	v_add_f32 v142, v64, v45
	v_add_f32 v138, v139, v140
	s_nop 0
	v_add_f32 v142, v142, v143
	v_add_f32 v143, v65, v46
	v_add_f32 v137, v137, v138
	s_nop 0
	v_add_f32 v143, v143, v144
	v_add_f32 v144, v136, v49
	v_add_f32 v138, v141, v142
	s_nop 0
	v_add_f32 v144, v144, v145
	s_nop 0
	v_add_f32 v139, v143, v144
	s_nop 0
	v_add_f32 v138, v138, v139
	s_nop 0
	v_add_f32 v137, v137, v138
	s_cbranch_vccz .LBB0_219
	v_sub_f32_e32 v133, v133, v34
	v_exp_f32_e32 v138, v133
	s_nop 0
	v_mul_f32_e32 v124, v124, v138
	v_pk_mul_f32 v[32:33], v[32:33], v[138:139] op_sel_hi:[1,0]
	v_pk_mul_f32 v[30:31], v[30:31], v[138:139] op_sel_hi:[1,0]
	v_pk_mul_f32 v[28:29], v[28:29], v[138:139] op_sel_hi:[1,0]
	v_pk_mul_f32 v[26:27], v[26:27], v[138:139] op_sel_hi:[1,0]
	v_pk_mul_f32 v[24:25], v[24:25], v[138:139] op_sel_hi:[1,0]
	v_pk_mul_f32 v[22:23], v[22:23], v[138:139] op_sel_hi:[1,0]
	v_pk_mul_f32 v[20:21], v[20:21], v[138:139] op_sel_hi:[1,0]
	v_pk_mul_f32 v[18:19], v[18:19], v[138:139] op_sel_hi:[1,0]
	v_pk_mul_f32 v[16:17], v[16:17], v[138:139] op_sel_hi:[1,0]
	v_pk_mul_f32 v[14:15], v[14:15], v[138:139] op_sel_hi:[1,0]
	v_pk_mul_f32 v[12:13], v[12:13], v[138:139] op_sel_hi:[1,0]
	v_pk_mul_f32 v[10:11], v[10:11], v[138:139] op_sel_hi:[1,0]
	v_pk_mul_f32 v[8:9], v[8:9], v[138:139] op_sel_hi:[1,0]
	v_pk_mul_f32 v[6:7], v[6:7], v[138:139] op_sel_hi:[1,0]
	v_pk_mul_f32 v[4:5], v[4:5], v[138:139] op_sel_hi:[1,0]
	v_pk_mul_f32 v[2:3], v[2:3], v[138:139] op_sel_hi:[1,0]

; DI void band_item(const Params& P, char* lds_blk, int layer, int bp) {
;     ...
;         for (int j = 0; j < 2; ++j) { *(u32x4*)(sK + (srow + 32 * j) * GP + sch * 16) = rk[j]; *(u32x4*)(sV + (srow + 32 * j) * GP + sch * 16) = rv[j]; }
;     ...
;         if (kt + 1 < 4) lstore(b ^ 1);
.LBB0_220:
	s_or_b64 exec, exec, s[0:1]
	s_andn2_b64 vcc, exec, s[22:23]
	s_cbranch_vccnz .LBB0_213
	s_xor_b32 s0, s70, 1
	s_mulk_i32 s0, 0x4800
	v_add_u32_e32 v34, s0, v130
	s_waitcnt vmcnt(0)
	ds_write_b128 v34, v[82:85]
	ds_write_b128 v34, v[86:89] offset:9216
	ds_write_b128 v34, v[90:93] offset:4608
	ds_write_b128 v34, v[94:97] offset:13824
	s_cmp_eq_u32 s65, 2
	s_cbranch_scc0 .Lb3_nost0
	s_cmp_eq_u32 s100, 1
	s_cbranch_scc0 .Lb3_nost0
	v_readfirstlane_b32 s0, v174
	s_nop 3
	s_lshr_b32 s0, s0, 8
	s_mul_i32 s0, s0, 0x5800
	s_sub_i32 s0, 0x14000, s0
	v_add_u32_e32 v254, s0, v130
	ds_write_b128 v254, v[238:241]
	ds_write_b128 v254, v[242:245] offset:9216
	ds_write_b128 v254, v[246:249] offset:4608
	ds_write_b128 v254, v[250:253] offset:13824
